# scan chunk loop: H-tile LDS reads issued before the next chunk's B*u MFMAs (LDS latency overlapped)
# speedup vs baseline: 1.0033x; 1.0033x over previous
.Lscr_noy:
	v_fma_f32 v15, -v131, v204, v15
	v_fma_f32 v47, v131, v28, v47
	v_fmac_f32_e32 v15, v252, v28
	v_fmac_f32_e32 v47, v252, v204
	v_cvt_pk_bf16_f32 v98, v15, v47
	ds_write_b32 v240, v98 offset:15536
	v_fma_f32 v14, -v131, v47, v14
	v_fma_f32 v46, v131, v15, v46
	v_fmac_f32_e32 v14, v252, v15
	v_fmac_f32_e32 v46, v252, v47
	v_cvt_pk_bf16_f32 v99, v14, v46
	ds_write_b32 v240, v99 offset:15264
	v_fma_f32 v13, -v131, v46, v13
	v_fma_f32 v45, v131, v14, v45
	v_fmac_f32_e32 v13, v252, v14
	v_fmac_f32_e32 v45, v252, v46
	v_cvt_pk_bf16_f32 v98, v13, v45
	ds_write_b32 v240, v98 offset:14992
	v_fma_f32 v12, -v131, v45, v12
	v_fma_f32 v44, v131, v13, v44
	v_fmac_f32_e32 v12, v252, v13
	v_fmac_f32_e32 v44, v252, v45
	v_cvt_pk_bf16_f32 v99, v12, v44
	ds_write_b32 v240, v99 offset:14720
	v_fma_f32 v27, -v131, v44, v27
	v_fma_f32 v203, v131, v12, v203
	v_fmac_f32_e32 v27, v252, v12
	v_fmac_f32_e32 v203, v252, v44
	v_cvt_pk_bf16_f32 v98, v27, v203
	ds_write_b32 v240, v98 offset:14448
	v_fma_f32 v26, -v131, v203, v26
	v_fma_f32 v202, v131, v27, v202
	v_fmac_f32_e32 v26, v252, v27
	v_fmac_f32_e32 v202, v252, v203
	v_cvt_pk_bf16_f32 v99, v26, v202
	ds_write_b32 v240, v99 offset:14176
	v_fma_f32 v25, -v131, v202, v25
	v_fma_f32 v201, v131, v26, v201
	v_fmac_f32_e32 v25, v252, v26
	v_fmac_f32_e32 v201, v252, v202
	v_cvt_pk_bf16_f32 v98, v25, v201
	ds_write_b32 v240, v98 offset:13904
	v_fma_f32 v24, -v131, v201, v24
	v_fma_f32 v200, v131, v25, v200
	v_fmac_f32_e32 v24, v252, v25
	v_fmac_f32_e32 v200, v252, v201
	v_cvt_pk_bf16_f32 v99, v24, v200
	ds_write_b32 v240, v99 offset:13632
	v_fma_f32 v11, -v131, v200, v11
	v_fma_f32 v43, v131, v24, v43
	v_fmac_f32_e32 v11, v252, v24
	v_fmac_f32_e32 v43, v252, v200
	v_cvt_pk_bf16_f32 v98, v11, v43
	ds_write_b32 v240, v98 offset:13360
	v_fma_f32 v10, -v131, v43, v10
	v_fma_f32 v42, v131, v11, v42
	v_fmac_f32_e32 v10, v252, v11
	v_fmac_f32_e32 v42, v252, v43
	v_cvt_pk_bf16_f32 v99, v10, v42
	ds_write_b32 v240, v99 offset:13088
	v_fma_f32 v9, -v131, v42, v9
	v_fma_f32 v41, v131, v10, v41
	v_fmac_f32_e32 v9, v252, v10
	v_fmac_f32_e32 v41, v252, v42
	v_cvt_pk_bf16_f32 v98, v9, v41
	ds_write_b32 v240, v98 offset:12816
	v_fma_f32 v8, -v131, v41, v8
	v_fma_f32 v40, v131, v9, v40
	v_fmac_f32_e32 v8, v252, v9
	v_fmac_f32_e32 v40, v252, v41
	v_cvt_pk_bf16_f32 v99, v8, v40
	ds_write_b32 v240, v99 offset:12544
	v_fma_f32 v23, -v131, v40, v23
	v_fma_f32 v199, v131, v8, v199
	v_fmac_f32_e32 v23, v252, v8
	v_fmac_f32_e32 v199, v252, v40
	v_cvt_pk_bf16_f32 v98, v23, v199
	ds_write_b32 v240, v98 offset:12272
	v_fma_f32 v22, -v131, v199, v22
	v_fma_f32 v198, v131, v23, v198
	v_fmac_f32_e32 v22, v252, v23
	v_fmac_f32_e32 v198, v252, v199
	v_cvt_pk_bf16_f32 v99, v22, v198
	ds_write_b32 v240, v99 offset:12000
	v_fma_f32 v21, -v131, v198, v21
	v_fma_f32 v197, v131, v22, v197
	v_fmac_f32_e32 v21, v252, v22
	v_fmac_f32_e32 v197, v252, v198
	v_cvt_pk_bf16_f32 v98, v21, v197
	ds_write_b32 v240, v98 offset:11728
	v_fma_f32 v20, -v131, v197, v20
	v_fma_f32 v196, v131, v21, v196
	v_fmac_f32_e32 v20, v252, v21
	v_fmac_f32_e32 v196, v252, v197
	v_cvt_pk_bf16_f32 v99, v20, v196
	ds_write_b32 v240, v99 offset:11456
	v_fma_f32 v7, -v131, v196, v7
	v_fma_f32 v39, v131, v20, v39
	v_fmac_f32_e32 v7, v252, v20
	v_fmac_f32_e32 v39, v252, v196
	v_cvt_pk_bf16_f32 v98, v7, v39
	ds_write_b32 v240, v98 offset:11184
	v_fma_f32 v6, -v131, v39, v6
	v_fma_f32 v38, v131, v7, v38
	v_fmac_f32_e32 v6, v252, v7
	v_fmac_f32_e32 v38, v252, v39
	v_cvt_pk_bf16_f32 v99, v6, v38
	ds_write_b32 v240, v99 offset:10912
	v_fma_f32 v5, -v131, v38, v5
	v_fma_f32 v37, v131, v6, v37
	v_fmac_f32_e32 v5, v252, v6
	v_fmac_f32_e32 v37, v252, v38
	v_cvt_pk_bf16_f32 v98, v5, v37
	ds_write_b32 v240, v98 offset:10640
	v_fma_f32 v4, -v131, v37, v4
	v_fma_f32 v36, v131, v5, v36
	v_fmac_f32_e32 v4, v252, v5
	v_fmac_f32_e32 v36, v252, v37
	v_cvt_pk_bf16_f32 v99, v4, v36
	ds_write_b32 v240, v99 offset:10368
	v_fma_f32 v19, -v131, v36, v19
	v_fma_f32 v195, v131, v4, v195
	v_fmac_f32_e32 v19, v252, v4
	v_fmac_f32_e32 v195, v252, v36
	v_cvt_pk_bf16_f32 v98, v19, v195
	ds_write_b32 v240, v98 offset:10096
	v_fma_f32 v18, -v131, v195, v18
	v_fma_f32 v194, v131, v19, v194
	v_fmac_f32_e32 v18, v252, v19
	v_fmac_f32_e32 v194, v252, v195
	v_cvt_pk_bf16_f32 v99, v18, v194
	ds_write_b32 v240, v99 offset:9824
	v_fma_f32 v17, -v131, v194, v17
	v_fma_f32 v193, v131, v18, v193
	v_fmac_f32_e32 v17, v252, v18
	v_fmac_f32_e32 v193, v252, v194
	v_cvt_pk_bf16_f32 v98, v17, v193
	ds_write_b32 v240, v98 offset:9552
	v_fma_f32 v16, -v131, v193, v16
	v_fma_f32 v192, v131, v17, v192
	v_fmac_f32_e32 v16, v252, v17
	v_fmac_f32_e32 v192, v252, v193
	v_cvt_pk_bf16_f32 v99, v16, v192
	ds_write_b32 v240, v99 offset:9280
	v_fma_f32 v3, -v131, v192, v3
	v_fma_f32 v35, v131, v16, v35
	v_fmac_f32_e32 v3, v252, v16
	v_fmac_f32_e32 v35, v252, v192
	v_cvt_pk_bf16_f32 v98, v3, v35
	ds_write_b32 v240, v98 offset:9008
	v_fma_f32 v2, -v131, v35, v2
	v_fma_f32 v34, v131, v3, v34
	v_fmac_f32_e32 v2, v252, v3
	v_fmac_f32_e32 v34, v252, v35
	v_cvt_pk_bf16_f32 v99, v2, v34
	ds_write_b32 v240, v99 offset:8736
	v_fma_f32 v1, -v131, v34, v1
	v_fma_f32 v33, v131, v2, v33
	v_fmac_f32_e32 v1, v252, v2
	v_fmac_f32_e32 v33, v252, v34
	v_cvt_pk_bf16_f32 v98, v1, v33
	ds_write_b32 v240, v98 offset:8464
	v_fma_f32 v174, -v131, v33, v0
	v_fma_f32 v175, v131, v1, v32
	v_fmac_f32_e32 v174, v252, v1
	v_fmac_f32_e32 v175, v252, v33
	v_cvt_pk_bf16_f32 v99, v174, v175
	ds_write_b32 v240, v99 offset:8192
	ds_read_b128 v[208:211], v241 offset:8192
	ds_read_b128 v[212:215], v241 offset:8224
	ds_read_b128 v[216:219], v241 offset:8256
	ds_read_b128 v[220:223], v241 offset:8288
	ds_read_b128 v[224:227], v241 offset:8320
	ds_read_b128 v[228:231], v241 offset:8352
	ds_read_b128 v[232:235], v241 offset:8384
	ds_read_b128 v[236:239], v241 offset:8416
	s_waitcnt vmcnt(2)
	v_mov_b64_e32 v[48:49], v[52:53]
	v_mov_b64_e32 v[50:51], v[54:55]
	s_cmp_lt_u32 s77, s39
	s_cselect_b32 s46, s48, 0
	s_cselect_b32 s47, s49, 0
	s_add_i32 s77, s77, 1
	v_lshl_add_u64 v[244:245], v[244:245], 0, s[46:47]
	global_load_dwordx4 v[52:55], v[244:245], off
	v_mfma_f32_32x32x16_bf16 v[0:15], v[48:51], v[110:113], 0
	v_mfma_f32_32x32x16_bf16 v[16:31], v[48:51], v[102:105], 0
	v_mfma_f32_32x32x16_bf16 v[32:47], v[48:51], v[106:109], 0
	v_mfma_f32_32x32x16_bf16 v[192:207], v[48:51], v[94:97], 0
	s_waitcnt lgkmcnt(7)
	v_mfma_f32_32x32x16_bf16 v[142:157], v[90:93], v[208:211], 0
	s_nop 6
	v_permlane32_swap_b32 v0, v16
	v_permlane32_swap_b32 v1, v17
	v_permlane32_swap_b32 v2, v18
	v_permlane32_swap_b32 v3, v19
	s_waitcnt lgkmcnt(6)
	v_mfma_f32_32x32x16_bf16 v[158:173], v[86:89], v[212:215], 0
	v_permlane32_swap_b32 v4, v20
	v_permlane32_swap_b32 v5, v21
	v_permlane32_swap_b32 v6, v22
	v_permlane32_swap_b32 v7, v23
	s_waitcnt lgkmcnt(5)
	v_mfma_f32_32x32x16_bf16 v[142:157], v[82:85], v[216:219], v[142:157]
	v_permlane32_swap_b32 v8, v24
	v_permlane32_swap_b32 v9, v25
	v_permlane32_swap_b32 v10, v26
	v_permlane32_swap_b32 v11, v27
	s_waitcnt lgkmcnt(4)
	v_mfma_f32_32x32x16_bf16 v[158:173], v[78:81], v[220:223], v[158:173]
	v_permlane32_swap_b32 v12, v28
	v_permlane32_swap_b32 v13, v29
	v_permlane32_swap_b32 v14, v30
	v_permlane32_swap_b32 v15, v31
	s_waitcnt lgkmcnt(3)
	v_mfma_f32_32x32x16_bf16 v[142:157], v[74:77], v[224:227], v[142:157]
	v_permlane32_swap_b32 v32, v192
	v_permlane32_swap_b32 v33, v193
	v_permlane32_swap_b32 v34, v194
	v_permlane32_swap_b32 v35, v195
	s_waitcnt lgkmcnt(2)
	v_mfma_f32_32x32x16_bf16 v[158:173], v[70:73], v[228:231], v[158:173]
	v_permlane32_swap_b32 v36, v196
	v_permlane32_swap_b32 v37, v197
	v_permlane32_swap_b32 v38, v198
	v_permlane32_swap_b32 v39, v199
	s_waitcnt lgkmcnt(1)
	v_mfma_f32_32x32x16_bf16 v[142:157], v[66:69], v[232:235], v[142:157]
	v_permlane32_swap_b32 v40, v200
	v_permlane32_swap_b32 v41, v201
	v_permlane32_swap_b32 v42, v202
	v_permlane32_swap_b32 v43, v203
	s_waitcnt lgkmcnt(0)
	v_mfma_f32_32x32x16_bf16 v[158:173], v[62:65], v[236:239], v[158:173]
	v_permlane32_swap_b32 v44, v204
	v_permlane32_swap_b32 v45, v205
	v_permlane32_swap_b32 v46, v206
	v_permlane32_swap_b32 v47, v207
	s_add_i32 s76, s76, 1
	s_cmp_lt_u32 s76, s39
	s_cbranch_scc1 .Lscr_loop
	s_nop 15
	v_add_f32_e32 v242, v142, v158
	v_add_f32_e32 v243, v143, v159
	v_add_f32_e32 v60, v144, v160
	v_add_f32_e32 v61, v145, v161
	v_add_f32_e32 v116, v146, v162
	v_add_f32_e32 v117, v147, v163
	v_add_f32_e32 v100, v148, v164
	v_add_f32_e32 v128, v149, v165
	v_cvt_pk_bf16_f32 v242, v242, v243
	v_cvt_pk_bf16_f32 v243, v60, v61
	v_cvt_pk_bf16_f32 v60, v116, v117
	v_cvt_pk_bf16_f32 v61, v100, v128
	global_store_dwordx2 v[246:247], v[242:243], off
	global_store_dwordx2 v[246:247], v[60:61], off offset:16
	v_lshl_add_u64 v[246:247], v[246:247], 0, s[48:49]
	v_mov_b32_e32 v114, v174
	v_mov_b32_e32 v115, v175
	s_branch .LBB0_629

.Lscf_noy:
	v_fma_f32 v16, -v131, v35, v16
	v_fma_f32 v192, v131, v3, v192
	v_fmac_f32_e32 v16, v252, v3
	v_fmac_f32_e32 v192, v252, v35
	v_cvt_pk_bf16_f32 v98, v16, v192
	ds_write_b32 v240, v98 offset:9280
	v_fma_f32 v17, -v131, v192, v17
	v_fma_f32 v193, v131, v16, v193
	v_fmac_f32_e32 v17, v252, v16
	v_fmac_f32_e32 v193, v252, v192
	v_cvt_pk_bf16_f32 v99, v17, v193
	ds_write_b32 v240, v99 offset:9552
	v_fma_f32 v18, -v131, v193, v18
	v_fma_f32 v194, v131, v17, v194
	v_fmac_f32_e32 v18, v252, v17
	v_fmac_f32_e32 v194, v252, v193
	v_cvt_pk_bf16_f32 v98, v18, v194
	ds_write_b32 v240, v98 offset:9824
	v_fma_f32 v19, -v131, v194, v19
	v_fma_f32 v195, v131, v18, v195
	v_fmac_f32_e32 v19, v252, v18
	v_fmac_f32_e32 v195, v252, v194
	v_cvt_pk_bf16_f32 v99, v19, v195
	ds_write_b32 v240, v99 offset:10096
	v_fma_f32 v4, -v131, v195, v4
	v_fma_f32 v36, v131, v19, v36
	v_fmac_f32_e32 v4, v252, v19
	v_fmac_f32_e32 v36, v252, v195
	v_cvt_pk_bf16_f32 v98, v4, v36
	ds_write_b32 v240, v98 offset:10368
	v_fma_f32 v5, -v131, v36, v5
	v_fma_f32 v37, v131, v4, v37
	v_fmac_f32_e32 v5, v252, v4
	v_fmac_f32_e32 v37, v252, v36
	v_cvt_pk_bf16_f32 v99, v5, v37
	ds_write_b32 v240, v99 offset:10640
	v_fma_f32 v6, -v131, v37, v6
	v_fma_f32 v38, v131, v5, v38
	v_fmac_f32_e32 v6, v252, v5
	v_fmac_f32_e32 v38, v252, v37
	v_cvt_pk_bf16_f32 v98, v6, v38
	ds_write_b32 v240, v98 offset:10912
	v_fma_f32 v7, -v131, v38, v7
	v_fma_f32 v39, v131, v6, v39
	v_fmac_f32_e32 v7, v252, v6
	v_fmac_f32_e32 v39, v252, v38
	v_cvt_pk_bf16_f32 v99, v7, v39
	ds_write_b32 v240, v99 offset:11184
	v_fma_f32 v20, -v131, v39, v20
	v_fma_f32 v196, v131, v7, v196
	v_fmac_f32_e32 v20, v252, v7
	v_fmac_f32_e32 v196, v252, v39
	v_cvt_pk_bf16_f32 v98, v20, v196
	ds_write_b32 v240, v98 offset:11456
	v_fma_f32 v21, -v131, v196, v21
	v_fma_f32 v197, v131, v20, v197
	v_fmac_f32_e32 v21, v252, v20
	v_fmac_f32_e32 v197, v252, v196
	v_cvt_pk_bf16_f32 v99, v21, v197
	ds_write_b32 v240, v99 offset:11728
	v_fma_f32 v22, -v131, v197, v22
	v_fma_f32 v198, v131, v21, v198
	v_fmac_f32_e32 v22, v252, v21
	v_fmac_f32_e32 v198, v252, v197
	v_cvt_pk_bf16_f32 v98, v22, v198
	ds_write_b32 v240, v98 offset:12000
	v_fma_f32 v23, -v131, v198, v23
	v_fma_f32 v199, v131, v22, v199
	v_fmac_f32_e32 v23, v252, v22
	v_fmac_f32_e32 v199, v252, v198
	v_cvt_pk_bf16_f32 v99, v23, v199
	ds_write_b32 v240, v99 offset:12272
	v_fma_f32 v8, -v131, v199, v8
	v_fma_f32 v40, v131, v23, v40
	v_fmac_f32_e32 v8, v252, v23
	v_fmac_f32_e32 v40, v252, v199
	v_cvt_pk_bf16_f32 v98, v8, v40
	ds_write_b32 v240, v98 offset:12544
	v_fma_f32 v9, -v131, v40, v9
	v_fma_f32 v41, v131, v8, v41
	v_fmac_f32_e32 v9, v252, v8
	v_fmac_f32_e32 v41, v252, v40
	v_cvt_pk_bf16_f32 v99, v9, v41
	ds_write_b32 v240, v99 offset:12816
	v_fma_f32 v10, -v131, v41, v10
	v_fma_f32 v42, v131, v9, v42
	v_fmac_f32_e32 v10, v252, v9
	v_fmac_f32_e32 v42, v252, v41
	v_cvt_pk_bf16_f32 v98, v10, v42
	ds_write_b32 v240, v98 offset:13088
	v_fma_f32 v11, -v131, v42, v11
	v_fma_f32 v43, v131, v10, v43
	v_fmac_f32_e32 v11, v252, v10
	v_fmac_f32_e32 v43, v252, v42
	v_cvt_pk_bf16_f32 v99, v11, v43
	ds_write_b32 v240, v99 offset:13360
	v_fma_f32 v24, -v131, v43, v24
	v_fma_f32 v200, v131, v11, v200
	v_fmac_f32_e32 v24, v252, v11
	v_fmac_f32_e32 v200, v252, v43
	v_cvt_pk_bf16_f32 v98, v24, v200
	ds_write_b32 v240, v98 offset:13632
	v_fma_f32 v25, -v131, v200, v25
	v_fma_f32 v201, v131, v24, v201
	v_fmac_f32_e32 v25, v252, v24
	v_fmac_f32_e32 v201, v252, v200
	v_cvt_pk_bf16_f32 v99, v25, v201
	ds_write_b32 v240, v99 offset:13904
	v_fma_f32 v26, -v131, v201, v26
	v_fma_f32 v202, v131, v25, v202
	v_fmac_f32_e32 v26, v252, v25
	v_fmac_f32_e32 v202, v252, v201
	v_cvt_pk_bf16_f32 v98, v26, v202
	ds_write_b32 v240, v98 offset:14176
	v_fma_f32 v27, -v131, v202, v27
	v_fma_f32 v203, v131, v26, v203
	v_fmac_f32_e32 v27, v252, v26
	v_fmac_f32_e32 v203, v252, v202
	v_cvt_pk_bf16_f32 v99, v27, v203
	ds_write_b32 v240, v99 offset:14448
	v_fma_f32 v12, -v131, v203, v12
	v_fma_f32 v44, v131, v27, v44
	v_fmac_f32_e32 v12, v252, v27
	v_fmac_f32_e32 v44, v252, v203
	v_cvt_pk_bf16_f32 v98, v12, v44
	ds_write_b32 v240, v98 offset:14720
	v_fma_f32 v13, -v131, v44, v13
	v_fma_f32 v45, v131, v12, v45
	v_fmac_f32_e32 v13, v252, v12
	v_fmac_f32_e32 v45, v252, v44
	v_cvt_pk_bf16_f32 v99, v13, v45
	ds_write_b32 v240, v99 offset:14992
	v_fma_f32 v14, -v131, v45, v14
	v_fma_f32 v46, v131, v13, v46
	v_fmac_f32_e32 v14, v252, v13
	v_fmac_f32_e32 v46, v252, v45
	v_cvt_pk_bf16_f32 v98, v14, v46
	ds_write_b32 v240, v98 offset:15264
	v_fma_f32 v15, -v131, v46, v15
	v_fma_f32 v47, v131, v14, v47
	v_fmac_f32_e32 v15, v252, v14
	v_fmac_f32_e32 v47, v252, v46
	v_cvt_pk_bf16_f32 v99, v15, v47
	ds_write_b32 v240, v99 offset:15536
	v_fma_f32 v28, -v131, v47, v28
	v_fma_f32 v204, v131, v15, v204
	v_fmac_f32_e32 v28, v252, v15
	v_fmac_f32_e32 v204, v252, v47
	v_cvt_pk_bf16_f32 v98, v28, v204
	ds_write_b32 v240, v98 offset:15808
	v_fma_f32 v29, -v131, v204, v29
	v_fma_f32 v205, v131, v28, v205
	v_fmac_f32_e32 v29, v252, v28
	v_fmac_f32_e32 v205, v252, v204
	v_cvt_pk_bf16_f32 v99, v29, v205
	ds_write_b32 v240, v99 offset:16080
	v_fma_f32 v30, -v131, v205, v30
	v_fma_f32 v206, v131, v29, v206
	v_fmac_f32_e32 v30, v252, v29
	v_fmac_f32_e32 v206, v252, v205
	v_cvt_pk_bf16_f32 v98, v30, v206
	ds_write_b32 v240, v98 offset:16352
	v_fma_f32 v174, -v131, v206, v31
	v_fma_f32 v175, v131, v30, v207
	v_fmac_f32_e32 v174, v252, v30
	v_fmac_f32_e32 v175, v252, v206
	v_cvt_pk_bf16_f32 v99, v174, v175
	ds_write_b32 v240, v99 offset:16624
	ds_read_b128 v[208:211], v241 offset:8192
	ds_read_b128 v[212:215], v241 offset:8224
	ds_read_b128 v[216:219], v241 offset:8256
	ds_read_b128 v[220:223], v241 offset:8288
	ds_read_b128 v[224:227], v241 offset:8320
	ds_read_b128 v[228:231], v241 offset:8352
	ds_read_b128 v[232:235], v241 offset:8384
	ds_read_b128 v[236:239], v241 offset:8416
	s_waitcnt vmcnt(2)
	v_mov_b64_e32 v[48:49], v[52:53]
	v_mov_b64_e32 v[50:51], v[54:55]
	s_cmp_lt_u32 s77, s39
	s_cselect_b32 s46, s48, 0
	s_cselect_b32 s47, s49, 0
	s_add_i32 s77, s77, 1
	v_lshl_add_u64 v[244:245], v[244:245], 0, s[46:47]
	global_load_dwordx4 v[52:55], v[244:245], off
	v_mfma_f32_32x32x16_bf16 v[0:15], v[48:51], v[110:113], 0
	v_mfma_f32_32x32x16_bf16 v[16:31], v[48:51], v[102:105], 0
	v_mfma_f32_32x32x16_bf16 v[32:47], v[48:51], v[106:109], 0
	v_mfma_f32_32x32x16_bf16 v[192:207], v[48:51], v[94:97], 0
	s_waitcnt lgkmcnt(7)
	v_mfma_f32_32x32x16_bf16 v[142:157], v[90:93], v[208:211], 0
	s_nop 6
	v_permlane32_swap_b32 v0, v16
	v_permlane32_swap_b32 v1, v17
	v_permlane32_swap_b32 v2, v18
	v_permlane32_swap_b32 v3, v19
	s_waitcnt lgkmcnt(6)
	v_mfma_f32_32x32x16_bf16 v[158:173], v[86:89], v[212:215], 0
	v_permlane32_swap_b32 v4, v20
	v_permlane32_swap_b32 v5, v21
	v_permlane32_swap_b32 v6, v22
	v_permlane32_swap_b32 v7, v23
	s_waitcnt lgkmcnt(5)
	v_mfma_f32_32x32x16_bf16 v[142:157], v[82:85], v[216:219], v[142:157]
	v_permlane32_swap_b32 v8, v24
	v_permlane32_swap_b32 v9, v25
	v_permlane32_swap_b32 v10, v26
	v_permlane32_swap_b32 v11, v27
	s_waitcnt lgkmcnt(4)
	v_mfma_f32_32x32x16_bf16 v[158:173], v[78:81], v[220:223], v[158:173]
	v_permlane32_swap_b32 v12, v28
	v_permlane32_swap_b32 v13, v29
	v_permlane32_swap_b32 v14, v30
	v_permlane32_swap_b32 v15, v31
	s_waitcnt lgkmcnt(3)
	v_mfma_f32_32x32x16_bf16 v[142:157], v[74:77], v[224:227], v[142:157]
	v_permlane32_swap_b32 v32, v192
	v_permlane32_swap_b32 v33, v193
	v_permlane32_swap_b32 v34, v194
	v_permlane32_swap_b32 v35, v195
	s_waitcnt lgkmcnt(2)
	v_mfma_f32_32x32x16_bf16 v[158:173], v[70:73], v[228:231], v[158:173]
	v_permlane32_swap_b32 v36, v196
	v_permlane32_swap_b32 v37, v197
	v_permlane32_swap_b32 v38, v198
	v_permlane32_swap_b32 v39, v199
	s_waitcnt lgkmcnt(1)
	v_mfma_f32_32x32x16_bf16 v[142:157], v[66:69], v[232:235], v[142:157]
	v_permlane32_swap_b32 v40, v200
	v_permlane32_swap_b32 v41, v201
	v_permlane32_swap_b32 v42, v202
	v_permlane32_swap_b32 v43, v203
	s_waitcnt lgkmcnt(0)
	v_mfma_f32_32x32x16_bf16 v[158:173], v[62:65], v[236:239], v[158:173]
	v_permlane32_swap_b32 v44, v204
	v_permlane32_swap_b32 v45, v205
	v_permlane32_swap_b32 v46, v206
	v_permlane32_swap_b32 v47, v207
	s_add_i32 s76, s76, 1
	s_cmp_lt_u32 s76, s39
	s_cbranch_scc1 .Lscf_loop
	s_nop 15
	v_add_f32_e32 v242, v142, v158
	v_add_f32_e32 v243, v143, v159
	v_add_f32_e32 v60, v144, v160
	v_add_f32_e32 v61, v145, v161
	v_add_f32_e32 v116, v146, v162
	v_add_f32_e32 v117, v147, v163
	v_add_f32_e32 v100, v148, v164
	v_add_f32_e32 v128, v149, v165
	v_cvt_pk_bf16_f32 v242, v242, v243
	v_cvt_pk_bf16_f32 v243, v60, v61
	v_cvt_pk_bf16_f32 v60, v116, v117
	v_cvt_pk_bf16_f32 v61, v100, v128
	global_store_dwordx2 v[246:247], v[242:243], off
	global_store_dwordx2 v[246:247], v[60:61], off offset:16
	v_lshl_add_u64 v[246:247], v[246:247], 0, s[48:49]
	v_mov_b32_e32 v135, v174
	v_mov_b32_e32 v101, v175
	s_branch .LBB0_631
